# tail workgroups (bx>=128) arrive at the barriers before S3 and before the GLU phase without waiting, complete them later (split barrier)
# speedup vs baseline: 1.0147x; 1.0084x over previous
.LBB0_793:
	s_mov_b32 s101, -1
	s_getreg_b32 s6, hwreg(HW_REG_XCC_ID, 0, 4)
	s_waitcnt vmcnt(0)
	s_barrier
	s_and_saveexec_b64 s[0:1], s[46:47]
	s_cbranch_execz .LBB0_910
	s_add_i32 s7, 0, 0x20160
	v_mov_b32_e32 v0, s7
	s_waitcnt vmcnt(0) expcnt(0) lgkmcnt(0)
	ds_read_b32 v2, v0
	s_add_i32 s7, 0, 0x20164
	v_mov_b32_e32 v0, s7
	ds_read_b32 v0, v0
	s_and_b32 s62, s6, 15
	s_waitcnt lgkmcnt(1)
	v_cmp_ne_u32_e32 vcc, 0, v2
	s_cbranch_vccnz .LBB0_874
	s_add_u32 s6, s66, 0x1200
	s_addc_u32 s7, s67, 0
	s_add_u32 s10, s66, 0x1400
	s_addc_u32 s11, s67, 0
	s_add_u32 s12, s66, 0x1500
	s_addc_u32 s13, s67, 0
	s_add_u32 s16, s66, 0x1600
	s_addc_u32 s17, s67, 0
	s_add_u32 s18, s66, 0x1700
	s_addc_u32 s19, s67, 0
	s_add_u32 s20, s66, 0x1800
	s_addc_u32 s21, s67, 0
	s_add_u32 s22, s66, 0x1900
	s_addc_u32 s23, s67, 0
	s_add_u32 s24, s66, 0x1a00
	s_addc_u32 s25, s67, 0
	s_add_u32 s26, s66, 0x1b00
	s_addc_u32 s27, s67, 0
	s_add_u32 s28, s66, 0x1c00
	s_addc_u32 s29, s67, 0
	s_add_u32 s30, s66, 0x1d00
	s_addc_u32 s31, s67, 0
	s_add_u32 s34, s66, 0x1e00
	s_addc_u32 s35, s67, 0
	s_add_u32 s36, s66, 0x1f00
	s_addc_u32 s37, s67, 0
	s_add_u32 s38, s66, 0x2000
	s_addc_u32 s39, s67, 0
	s_add_u32 s40, s66, 0x2100
	s_addc_u32 s41, s67, 0
	s_add_u32 s42, s66, 0x2200
	s_addc_u32 s43, s67, 0
	s_mul_i32 s63, s65, s74
	s_add_u32 s44, s66, 0x2300
	s_mul_i32 s63, s63, s64
	s_addc_u32 s45, s67, 0
	s_mov_b32 s70, 1
	v_mov_b32_e32 v16, 0
	s_branch .LBB0_862

.LBB0_876:
	s_or_b64 exec, exec, s[12:13]
	v_cvt_f32_u32_e32 v4, v2
	s_waitcnt vmcnt(0)
	v_readfirstlane_b32 s10, v3
	v_sub_u32_e32 v3, 0, v2
	v_rcp_iflag_f32_e32 v4, v4
	v_add_u32_e32 v5, s10, v1
	v_mul_f32_e32 v4, 0x4f7ffffe, v4
	v_cvt_u32_f32_e32 v4, v4
	v_mul_lo_u32 v1, v3, v4
	v_mul_hi_u32 v1, v4, v1
	v_add_u32_e32 v1, v4, v1
	v_mul_hi_u32 v1, v5, v1
	v_mul_lo_u32 v3, v1, v2
	v_sub_u32_e32 v3, v5, v3
	v_add_u32_e32 v4, 1, v1
	v_cmp_ge_u32_e32 vcc, v3, v2
	s_nop 1
	v_cndmask_b32_e32 v1, v1, v4, vcc
	v_sub_u32_e32 v4, v3, v2
	v_cndmask_b32_e32 v3, v3, v4, vcc
	v_add_u32_e32 v4, 1, v1
	v_cmp_ge_u32_e32 vcc, v3, v2
	v_add_u32_e32 v3, 1, v5
	s_nop 0
	v_cndmask_b32_e32 v1, v1, v4, vcc
	v_mul_lo_u32 v4, v2, v1
	v_add_u32_e32 v2, v4, v2
	v_cmp_ne_u32_e32 vcc, v3, v2
	s_and_saveexec_b64 s[10:11], vcc
	s_xor_b64 s[10:11], exec, s[10:11]
	s_cbranch_execz .LBB0_890
	s_cmp_lt_u32 s2, 0x80
	s_cbranch_scc1 .Lsb_wait_a0
	s_cmp_lg_u32 s64, 0x100
	s_cbranch_scc1 .Lsb_wait_a0
	v_readfirstlane_b32 s101, v1
	s_branch .LBB0_890
.Lsb_wait_a0:
	s_waitcnt lgkmcnt(0)
	buffer_inv sc1
	v_mov_b32_e32 v0, 0x2000
	global_load_dword v0, v0, s[6:7] offset:1024 sc1
	s_add_u32 s18, s6, 0x2400
	s_addc_u32 s19, s7, 0
	s_waitcnt vmcnt(0)
	v_cmp_eq_u32_e32 vcc, v0, v1
	s_and_saveexec_b64 s[12:13], vcc
	s_cbranch_execz .LBB0_889
	s_add_u32 s16, s66, 0x1200
	s_addc_u32 s17, s67, 0
	s_mov_b32 s30, 1
	s_mov_b64 s[20:21], 0
	v_mov_b32_e32 v0, 0
	s_branch .LBB0_880

.LBB0_954:
	s_and_saveexec_b64 s[0:1], s[46:47]
	s_cbranch_execz .Lsb_cj_a0
	s_cmp_eq_u32 s101, -1
	s_cbranch_scc1 .Lsb_cj_a0
	s_getreg_b32 s98, hwreg(HW_REG_XCC_ID, 0, 4)
	s_lshl_b32 s98, s98, 8
	s_add_i32 s98, s98, 0x3400
	v_mov_b32_e32 v250, s98
	s_mov_b32 s99, 0
.Lsb_spin_a0:
	global_load_dword v251, v250, s[66:67] sc1
	s_waitcnt vmcnt(0)
	v_readfirstlane_b32 s98, v251
	s_cmp_lg_u32 s98, s101
	s_cbranch_scc1 .Lsb_rel_a0
	s_sleep 1
	s_add_i32 s99, s99, 1
	s_cmp_lt_u32 s99, 0x40000
	s_cbranch_scc1 .Lsb_spin_a0
.Lsb_rel_a0:
	buffer_inv sc1
	s_waitcnt vmcnt(0)
	s_mov_b32 s101, -1
.Lsb_cj_a0:
	s_or_b64 exec, exec, s[0:1]
	s_barrier
	s_mov_b32 s101, -1
	s_getreg_b32 s6, hwreg(HW_REG_XCC_ID, 0, 4)
	s_waitcnt vmcnt(0)
	s_waitcnt vmcnt(0)
	s_barrier
	s_and_saveexec_b64 s[0:1], s[46:47]
	s_cbranch_execz .LBB0_1006
	s_add_i32 s7, 0, 0x20160
	v_mov_b32_e32 v0, s7
	s_waitcnt vmcnt(0) expcnt(0) lgkmcnt(0)
	ds_read_b32 v2, v0
	s_add_i32 s7, 0, 0x20164
	v_mov_b32_e32 v0, s7
	ds_read_b32 v0, v0
	s_and_b32 s51, s6, 15
	s_waitcnt lgkmcnt(1)
	v_cmp_ne_u32_e32 vcc, 0, v2
	s_cbranch_vccnz .LBB0_970
	s_add_u32 s6, s66, 0x1200
	s_addc_u32 s7, s67, 0
	s_add_u32 s10, s66, 0x1400
	s_addc_u32 s11, s67, 0
	s_add_u32 s16, s66, 0x1500
	s_addc_u32 s17, s67, 0
	s_add_u32 s18, s66, 0x1600
	s_addc_u32 s19, s67, 0
	s_add_u32 s20, s66, 0x1700
	s_addc_u32 s21, s67, 0
	s_add_u32 s22, s66, 0x1800
	s_addc_u32 s23, s67, 0
	s_add_u32 s24, s66, 0x1900
	s_addc_u32 s25, s67, 0
	s_add_u32 s26, s66, 0x1a00
	s_addc_u32 s27, s67, 0
	s_add_u32 s28, s66, 0x1b00
	s_addc_u32 s29, s67, 0
	s_add_u32 s30, s66, 0x1c00
	s_addc_u32 s31, s67, 0
	s_add_u32 s34, s66, 0x1d00
	s_addc_u32 s35, s67, 0
	s_add_u32 s36, s66, 0x1e00
	s_addc_u32 s37, s67, 0
	s_add_u32 s38, s66, 0x1f00
	s_addc_u32 s39, s67, 0
	s_add_u32 s40, s66, 0x2000
	s_addc_u32 s41, s67, 0
	s_add_u32 s42, s66, 0x2100
	s_addc_u32 s43, s67, 0
	s_add_u32 s44, s66, 0x2200
	s_addc_u32 s45, s67, 0
	s_mul_i32 s72, s65, s74
	s_add_u32 s58, s66, 0x2300
	s_mul_i32 s72, s72, s64
	s_addc_u32 s59, s67, 0
	s_mov_b32 s73, 1
	v_mov_b32_e32 v16, 0
	s_branch .LBB0_958

.LBB0_972:
	s_or_b64 exec, exec, s[16:17]
	v_cvt_f32_u32_e32 v4, v2
	s_waitcnt vmcnt(0)
	v_readfirstlane_b32 s10, v3
	v_sub_u32_e32 v3, 0, v2
	v_rcp_iflag_f32_e32 v4, v4
	v_add_u32_e32 v5, s10, v1
	v_mul_f32_e32 v4, 0x4f7ffffe, v4
	v_cvt_u32_f32_e32 v4, v4
	v_mul_lo_u32 v1, v3, v4
	v_mul_hi_u32 v1, v4, v1
	v_add_u32_e32 v1, v4, v1
	v_mul_hi_u32 v1, v5, v1
	v_mul_lo_u32 v3, v1, v2
	v_sub_u32_e32 v3, v5, v3
	v_add_u32_e32 v4, 1, v1
	v_cmp_ge_u32_e32 vcc, v3, v2
	s_nop 1
	v_cndmask_b32_e32 v1, v1, v4, vcc
	v_sub_u32_e32 v4, v3, v2
	v_cndmask_b32_e32 v3, v3, v4, vcc
	v_add_u32_e32 v4, 1, v1
	v_cmp_ge_u32_e32 vcc, v3, v2
	v_add_u32_e32 v3, 1, v5
	s_nop 0
	v_cndmask_b32_e32 v1, v1, v4, vcc
	v_mul_lo_u32 v4, v2, v1
	v_add_u32_e32 v2, v4, v2
	v_cmp_ne_u32_e32 vcc, v3, v2
	s_and_saveexec_b64 s[10:11], vcc
	s_xor_b64 s[10:11], exec, s[10:11]
	s_cbranch_execz .LBB0_986
	s_cmp_lt_u32 s2, 0x80
	s_cbranch_scc1 .Lsb_wait_b0
	s_cmp_lg_u32 s64, 0x100
	s_cbranch_scc1 .Lsb_wait_b0
	v_readfirstlane_b32 s101, v1
	s_branch .LBB0_986
.Lsb_wait_b0:
	s_waitcnt lgkmcnt(0)
	buffer_inv sc1
	v_mov_b32_e32 v0, 0x2000
	global_load_dword v0, v0, s[6:7] offset:1024 sc1
	s_add_u32 s20, s6, 0x2400
	s_addc_u32 s21, s7, 0
	s_waitcnt vmcnt(0)
	v_cmp_eq_u32_e32 vcc, v0, v1
	s_and_saveexec_b64 s[16:17], vcc
	s_cbranch_execz .LBB0_985
	s_add_u32 s18, s66, 0x1200
	s_addc_u32 s19, s67, 0
	s_mov_b32 s34, 1
	s_mov_b64 s[22:23], 0
	v_mov_b32_e32 v0, 0
	s_branch .LBB0_976

.LBB0_1054:
	s_waitcnt vmcnt(0)
	s_barrier
	s_and_saveexec_b64 s[0:1], s[46:47]
	s_cbranch_execz .Lsb_cj_b0
	s_cmp_eq_u32 s101, -1
	s_cbranch_scc1 .Lsb_cj_b0
	s_getreg_b32 s98, hwreg(HW_REG_XCC_ID, 0, 4)
	s_lshl_b32 s98, s98, 8
	s_add_i32 s98, s98, 0x3400
	v_mov_b32_e32 v250, s98
	s_mov_b32 s99, 0

.Lsb_cj_b0:
	s_or_b64 exec, exec, s[0:1]
	s_barrier
	s_mov_b64 s[28:29], s[66:67]
	s_waitcnt lgkmcnt(0)
	s_barrier
	s_mov_b64 s[0:1], s[68:69]
	v_mov_b32_e32 v36, v194
	s_add_u32 s26, s28, 0x5800000
	v_cndmask_b32_e64 v0, 0, 1, s[14:15]
	s_mov_b32 s40, s64
	v_readfirstlane_b32 s41, v36
	s_addc_u32 s27, s29, 0
	v_cmp_ne_u32_e64 s[12:13], 1, v0
	s_andn2_b64 vcc, exec, s[14:15]
	v_and_b32_e32 v39, 15, v36
	s_cbranch_vccnz .LBB0_1108
	v_and_b32_e32 v10, 15, v36
	s_cbranch_execz .LBB0_1109
	s_branch .LBB0_1118

.LBB0_2403:
	s_mov_b32 s101, -1
	s_getreg_b32 s8, hwreg(HW_REG_XCC_ID, 0, 4)
	s_waitcnt vmcnt(0)
	s_barrier
	s_and_saveexec_b64 s[0:1], s[46:47]
	s_cbranch_execz .LBB0_2520
	s_add_i32 s9, 0, 0x20160
	v_mov_b32_e32 v0, s9
	s_waitcnt vmcnt(0) expcnt(0) lgkmcnt(0)
	ds_read_b32 v2, v0
	s_add_i32 s9, 0, 0x20164
	v_mov_b32_e32 v0, s9
	ds_read_b32 v0, v0
	s_and_b32 s51, s8, 15
	s_waitcnt lgkmcnt(1)
	v_cmp_ne_u32_e32 vcc, 0, v2
	s_cbranch_vccnz .LBB0_2484
	s_add_u32 s8, s66, 0x1200
	s_addc_u32 s9, s67, 0
	s_add_u32 s14, s66, 0x1400
	s_addc_u32 s15, s67, 0
	s_add_u32 s16, s66, 0x1500
	s_addc_u32 s17, s67, 0
	s_add_u32 s18, s66, 0x1600
	s_addc_u32 s19, s67, 0
	s_add_u32 s20, s66, 0x1700
	s_addc_u32 s21, s67, 0
	s_add_u32 s22, s66, 0x1800
	s_addc_u32 s23, s67, 0
	s_add_u32 s24, s66, 0x1900
	s_addc_u32 s25, s67, 0
	s_add_u32 s26, s66, 0x1a00
	s_addc_u32 s27, s67, 0
	s_add_u32 s28, s66, 0x1b00
	s_addc_u32 s29, s67, 0
	s_add_u32 s30, s66, 0x1c00
	s_addc_u32 s31, s67, 0
	s_add_u32 s34, s66, 0x1d00
	s_addc_u32 s35, s67, 0
	s_add_u32 s36, s66, 0x1e00
	s_addc_u32 s37, s67, 0
	s_add_u32 s38, s66, 0x1f00
	s_addc_u32 s39, s67, 0
	s_add_u32 s40, s66, 0x2000
	s_addc_u32 s41, s67, 0
	s_add_u32 s42, s66, 0x2100
	s_addc_u32 s43, s67, 0
	s_add_u32 s44, s66, 0x2200
	s_addc_u32 s45, s67, 0
	s_mul_i32 s58, s65, s74
	s_add_u32 s48, s66, 0x2300
	s_mul_i32 s58, s58, s64
	s_addc_u32 s49, s67, 0
	s_mov_b32 s59, 1
	v_mov_b32_e32 v16, 0
	s_branch .LBB0_2472

.LBB0_2486:
	s_or_b64 exec, exec, s[16:17]
	v_cvt_f32_u32_e32 v4, v2
	s_waitcnt vmcnt(0)
	v_readfirstlane_b32 s14, v3
	v_sub_u32_e32 v3, 0, v2
	v_rcp_iflag_f32_e32 v4, v4
	v_add_u32_e32 v5, s14, v1
	v_mul_f32_e32 v4, 0x4f7ffffe, v4
	v_cvt_u32_f32_e32 v4, v4
	v_mul_lo_u32 v1, v3, v4
	v_mul_hi_u32 v1, v4, v1
	v_add_u32_e32 v1, v4, v1
	v_mul_hi_u32 v1, v5, v1
	v_mul_lo_u32 v3, v1, v2
	v_sub_u32_e32 v3, v5, v3
	v_add_u32_e32 v4, 1, v1
	v_cmp_ge_u32_e32 vcc, v3, v2
	s_nop 1
	v_cndmask_b32_e32 v1, v1, v4, vcc
	v_sub_u32_e32 v4, v3, v2
	v_cndmask_b32_e32 v3, v3, v4, vcc
	v_add_u32_e32 v4, 1, v1
	v_cmp_ge_u32_e32 vcc, v3, v2
	v_add_u32_e32 v3, 1, v5
	s_nop 0
	v_cndmask_b32_e32 v1, v1, v4, vcc
	v_mul_lo_u32 v4, v2, v1
	v_add_u32_e32 v2, v4, v2
	v_cmp_ne_u32_e32 vcc, v3, v2
	s_and_saveexec_b64 s[14:15], vcc
	s_xor_b64 s[14:15], exec, s[14:15]
	s_cbranch_execz .LBB0_2500
	s_cmp_lt_u32 s2, 0x80
	s_cbranch_scc1 .Lsb_wait_a1
	s_cmp_lg_u32 s64, 0x100
	s_cbranch_scc1 .Lsb_wait_a1
	v_readfirstlane_b32 s101, v1
	s_branch .LBB0_2500
.Lsb_wait_a1:
	s_waitcnt lgkmcnt(0)
	buffer_inv sc1
	v_mov_b32_e32 v0, 0x2000
	global_load_dword v0, v0, s[8:9] offset:1024 sc1
	s_add_u32 s20, s8, 0x2400
	s_addc_u32 s21, s9, 0
	s_waitcnt vmcnt(0)
	v_cmp_eq_u32_e32 vcc, v0, v1
	s_and_saveexec_b64 s[16:17], vcc
	s_cbranch_execz .LBB0_2499
	s_add_u32 s18, s66, 0x1200
	s_addc_u32 s19, s67, 0
	s_mov_b32 s34, 1
	s_mov_b64 s[22:23], 0
	v_mov_b32_e32 v0, 0
	s_branch .LBB0_2490

.Lsb_cj_a1:
	s_or_b64 exec, exec, s[0:1]
	s_barrier
	s_mov_b32 s101, -1
	s_getreg_b32 s8, hwreg(HW_REG_XCC_ID, 0, 4)
	s_waitcnt vmcnt(0)
	s_waitcnt vmcnt(0)
	s_barrier
	s_and_saveexec_b64 s[0:1], s[46:47]
	s_cbranch_execz .LBB0_2616
	s_add_i32 s9, 0, 0x20160
	v_mov_b32_e32 v0, s9
	s_waitcnt vmcnt(0) expcnt(0) lgkmcnt(0)
	ds_read_b32 v2, v0
	s_add_i32 s9, 0, 0x20164
	v_mov_b32_e32 v0, s9
	ds_read_b32 v0, v0
	s_and_b32 s51, s8, 15
	s_waitcnt lgkmcnt(1)
	v_cmp_ne_u32_e32 vcc, 0, v2
	s_cbranch_vccnz .LBB0_2580
	s_add_u32 s8, s66, 0x1200
	s_addc_u32 s9, s67, 0
	s_add_u32 s14, s66, 0x1400
	s_addc_u32 s15, s67, 0
	s_add_u32 s16, s66, 0x1500
	s_addc_u32 s17, s67, 0
	s_add_u32 s18, s66, 0x1600
	s_addc_u32 s19, s67, 0
	s_add_u32 s20, s66, 0x1700
	s_addc_u32 s21, s67, 0
	s_add_u32 s22, s66, 0x1800
	s_addc_u32 s23, s67, 0
	s_add_u32 s24, s66, 0x1900
	s_addc_u32 s25, s67, 0
	s_add_u32 s26, s66, 0x1a00
	s_addc_u32 s27, s67, 0
	s_add_u32 s28, s66, 0x1b00
	s_addc_u32 s29, s67, 0
	s_add_u32 s30, s66, 0x1c00
	s_addc_u32 s31, s67, 0
	s_add_u32 s34, s66, 0x1d00
	s_addc_u32 s35, s67, 0
	s_add_u32 s36, s66, 0x1e00
	s_addc_u32 s37, s67, 0
	s_add_u32 s38, s66, 0x1f00
	s_addc_u32 s39, s67, 0
	s_add_u32 s40, s66, 0x2000
	s_addc_u32 s41, s67, 0
	s_add_u32 s42, s66, 0x2100
	s_addc_u32 s43, s67, 0
	s_add_u32 s44, s66, 0x2200
	s_addc_u32 s45, s67, 0
	s_mul_i32 s58, s65, s74
	s_add_u32 s48, s66, 0x2300
	s_mul_i32 s58, s58, s64
	s_addc_u32 s49, s67, 0
	s_mov_b32 s59, 1
	v_mov_b32_e32 v16, 0
	s_branch .LBB0_2568

.Lsb_cj_b1:
	s_or_b64 exec, exec, s[0:1]
	s_barrier
	s_mov_b64 s[24:25], s[66:67]
	s_waitcnt lgkmcnt(0)
	s_barrier
	s_mov_b64 s[0:1], s[68:69]
	v_mov_b32_e32 v36, v194
	s_add_u32 s22, s24, 0x5800000
	s_mov_b32 s36, s64
	v_readfirstlane_b32 s37, v36
	s_addc_u32 s23, s25, 0
	s_and_b64 vcc, exec, s[12:13]
	v_and_b32_e32 v39, 15, v36
	s_cbranch_vccnz .LBB0_2718
	v_and_b32_e32 v10, 15, v36
	s_cbranch_execz .LBB0_2719
	s_branch .LBB0_2728
